# output-projection epilogue (residual add): residual loads issued two row-blocks ahead into dead fragment registers with counted waits, so no wait covers the previous block's stores
# baseline (speedup 1.0000x reference)
;     __device__ __forceinline__ void operator()(const f32x4 (&acc)[2][2][4][2], const Unit& u, int wr, int wc, int fr, int fq) const {
;         const int row0 = u.pm * BM + wr * 64 + fr; const int col0 = u.pn * BM + wc * 32 + 8 * fq;
; #pragma unroll
;         for (int ai = 0; ai < 2; ++ai)
; #pragma unroll
;             for (int m = 0; m < 4; ++m) { const size_t row = (size_t)(row0 + ai * HALF + m * 16);
; #pragma unroll
;                 for (int bj = 0; bj < 2; ++bj) { const size_t off = row * 1024 + col0 + bj * HALF;
;                     const f32x4 x0 = *(const f32x4*)(xin + off), x1 = *(const f32x4*)(xin + off + 4);
;                     *(f32x4*)(out + off) = x0 + acc[ai][bj][m][0]; *(f32x4*)(out + off + 4) = x1 + acc[ai][bj][m][1]; } }
;     }
.LBB0_241:
	v_lshl_add_u32 v144, s21, 8, v146
	v_lshl_or_b32 v142, s20, 8, v148
	v_ashrrev_i32_e32 v145, 31, v144
	v_ashrrev_i32_e32 v143, 31, v142
	v_lshlrev_b64 v[140:141], 10, v[144:145]
	v_lshl_add_u64 v[140:141], v[140:141], 0, v[142:143]
	v_readlane_b32 s22, v255, 7
	v_lshlrev_b64 v[140:141], 2, v[140:141]
	v_readlane_b32 s23, v255, 8
	v_readlane_b32 s48, v255, 9
	v_readlane_b32 s49, v255, 10
	v_lshl_add_u64 v[158:159], s[22:23], 0, v[140:141]
	s_mov_b64 s[20:21], 0
	v_lshl_add_u64 v[234:235], v[140:141], 0, s[20:21]
	v_lshl_add_u64 v[230:231], s[22:23], 0, v[234:235]
	global_load_dwordx4 v[150:153], v[230:231], off
	global_load_dwordx4 v[154:157], v[230:231], off offset:16
	global_load_dwordx4 v[158:161], v[230:231], off offset:512
	global_load_dwordx4 v[162:165], v[230:231], off offset:528
	s_mov_b64 s[20:21], 0x10000
	v_lshl_add_u64 v[234:235], v[140:141], 0, s[20:21]
	v_lshl_add_u64 v[230:231], s[22:23], 0, v[234:235]
	global_load_dwordx4 v[166:169], v[230:231], off
	global_load_dwordx4 v[170:173], v[230:231], off offset:16
	global_load_dwordx4 v[174:177], v[230:231], off offset:512
	global_load_dwordx4 v[178:181], v[230:231], off offset:528
	s_mov_b64 s[20:21], 0x20000
	v_lshl_add_u64 v[234:235], v[140:141], 0, s[20:21]
	v_lshl_add_u64 v[230:231], s[22:23], 0, v[234:235]
	global_load_dwordx4 v[182:185], v[230:231], off
	global_load_dwordx4 v[186:189], v[230:231], off offset:16
	global_load_dwordx4 v[218:221], v[230:231], off offset:512
	global_load_dwordx4 v[222:225], v[230:231], off offset:528
	s_mov_b64 s[20:21], 0
	v_lshl_add_u64 v[234:235], v[140:141], 0, s[20:21]
	v_lshl_add_u64 v[232:233], s[48:49], 0, v[234:235]
	s_waitcnt vmcnt(8)
	v_pk_add_f32 v[126:127], v[126:127], v[150:151]
	v_pk_add_f32 v[128:129], v[128:129], v[152:153]
	global_store_dwordx4 v[232:233], v[126:129], off
	v_pk_add_f32 v[122:123], v[122:123], v[154:155]
	v_pk_add_f32 v[124:125], v[124:125], v[156:157]
	global_store_dwordx4 v[232:233], v[122:125], off offset:16
	v_pk_add_f32 v[118:119], v[118:119], v[158:159]
	v_pk_add_f32 v[120:121], v[120:121], v[160:161]
	global_store_dwordx4 v[232:233], v[118:121], off offset:512
	v_pk_add_f32 v[114:115], v[114:115], v[162:163]
	v_pk_add_f32 v[116:117], v[116:117], v[164:165]
	global_store_dwordx4 v[232:233], v[114:117], off offset:528
	s_mov_b64 s[20:21], 0x30000
	v_lshl_add_u64 v[234:235], v[140:141], 0, s[20:21]
	v_lshl_add_u64 v[230:231], s[22:23], 0, v[234:235]
	global_load_dwordx4 v[150:153], v[230:231], off
	global_load_dwordx4 v[154:157], v[230:231], off offset:16
	global_load_dwordx4 v[158:161], v[230:231], off offset:512
	global_load_dwordx4 v[162:165], v[230:231], off offset:528
	s_mov_b64 s[20:21], 0x10000
	v_lshl_add_u64 v[234:235], v[140:141], 0, s[20:21]
	v_lshl_add_u64 v[232:233], s[48:49], 0, v[234:235]
	s_waitcnt vmcnt(12)
	v_pk_add_f32 v[110:111], v[110:111], v[166:167]
	v_pk_add_f32 v[112:113], v[112:113], v[168:169]
	global_store_dwordx4 v[232:233], v[110:113], off
	v_pk_add_f32 v[106:107], v[106:107], v[170:171]
	v_pk_add_f32 v[108:109], v[108:109], v[172:173]
	global_store_dwordx4 v[232:233], v[106:109], off offset:16
	v_pk_add_f32 v[102:103], v[102:103], v[174:175]
	v_pk_add_f32 v[104:105], v[104:105], v[176:177]
	global_store_dwordx4 v[232:233], v[102:105], off offset:512
	v_pk_add_f32 v[98:99], v[98:99], v[178:179]
	v_pk_add_f32 v[100:101], v[100:101], v[180:181]
	global_store_dwordx4 v[232:233], v[98:101], off offset:528
	s_mov_b64 s[20:21], 0x80000
	v_lshl_add_u64 v[234:235], v[140:141], 0, s[20:21]
	v_lshl_add_u64 v[230:231], s[22:23], 0, v[234:235]
	global_load_dwordx4 v[166:169], v[230:231], off
	global_load_dwordx4 v[170:173], v[230:231], off offset:16
	global_load_dwordx4 v[174:177], v[230:231], off offset:512
	global_load_dwordx4 v[178:181], v[230:231], off offset:528
	s_mov_b64 s[20:21], 0x20000
	v_lshl_add_u64 v[234:235], v[140:141], 0, s[20:21]
	v_lshl_add_u64 v[232:233], s[48:49], 0, v[234:235]
	s_waitcnt vmcnt(16)
	v_pk_add_f32 v[94:95], v[94:95], v[182:183]
	v_pk_add_f32 v[96:97], v[96:97], v[184:185]
	global_store_dwordx4 v[232:233], v[94:97], off
	v_pk_add_f32 v[90:91], v[90:91], v[186:187]
	v_pk_add_f32 v[92:93], v[92:93], v[188:189]
	global_store_dwordx4 v[232:233], v[90:93], off offset:16
	v_pk_add_f32 v[86:87], v[86:87], v[218:219]
	v_pk_add_f32 v[88:89], v[88:89], v[220:221]
	global_store_dwordx4 v[232:233], v[86:89], off offset:512
	v_pk_add_f32 v[82:83], v[82:83], v[222:223]
	v_pk_add_f32 v[84:85], v[84:85], v[224:225]
	global_store_dwordx4 v[232:233], v[82:85], off offset:528
	s_mov_b64 s[20:21], 0x90000
	v_lshl_add_u64 v[234:235], v[140:141], 0, s[20:21]
	v_lshl_add_u64 v[230:231], s[22:23], 0, v[234:235]
	global_load_dwordx4 v[182:185], v[230:231], off
	global_load_dwordx4 v[186:189], v[230:231], off offset:16
	global_load_dwordx4 v[218:221], v[230:231], off offset:512
	global_load_dwordx4 v[222:225], v[230:231], off offset:528
	s_mov_b64 s[20:21], 0x30000
	v_lshl_add_u64 v[234:235], v[140:141], 0, s[20:21]
	v_lshl_add_u64 v[232:233], s[48:49], 0, v[234:235]
	s_waitcnt vmcnt(16)
;     __device__ __forceinline__ void operator()(const f32x4 (&acc)[2][2][4][2], const Unit& u, int wr, int wc, int fr, int fq) const {
;         const int row0 = u.pm * BM + wr * 64 + fr; const int col0 = u.pn * BM + wc * 32 + 8 * fq;
; #pragma unroll
;         for (int ai = 0; ai < 2; ++ai)
; #pragma unroll
;             for (int m = 0; m < 4; ++m) { const size_t row = (size_t)(row0 + ai * HALF + m * 16);
; #pragma unroll
;                 for (int bj = 0; bj < 2; ++bj) { const size_t off = row * 1024 + col0 + bj * HALF;
;                     const f32x4 x0 = *(const f32x4*)(xin + off), x1 = *(const f32x4*)(xin + off + 4);
;                     *(f32x4*)(out + off) = x0 + acc[ai][bj][m][0]; *(f32x4*)(out + off + 4) = x1 + acc[ai][bj][m][1]; } }
;     }
	v_pk_add_f32 v[78:79], v[78:79], v[150:151]
	v_pk_add_f32 v[80:81], v[80:81], v[152:153]
	global_store_dwordx4 v[232:233], v[78:81], off
	v_pk_add_f32 v[74:75], v[74:75], v[154:155]
	v_pk_add_f32 v[76:77], v[76:77], v[156:157]
	global_store_dwordx4 v[232:233], v[74:77], off offset:16
	v_pk_add_f32 v[70:71], v[70:71], v[158:159]
	v_pk_add_f32 v[72:73], v[72:73], v[160:161]
	global_store_dwordx4 v[232:233], v[70:73], off offset:512
	v_pk_add_f32 v[66:67], v[66:67], v[162:163]
	v_pk_add_f32 v[68:69], v[68:69], v[164:165]
	global_store_dwordx4 v[232:233], v[66:69], off offset:528
	s_mov_b64 s[20:21], 0xa0000
	v_lshl_add_u64 v[234:235], v[140:141], 0, s[20:21]
	v_lshl_add_u64 v[230:231], s[22:23], 0, v[234:235]
	global_load_dwordx4 v[150:153], v[230:231], off
	global_load_dwordx4 v[154:157], v[230:231], off offset:16
	global_load_dwordx4 v[158:161], v[230:231], off offset:512
	global_load_dwordx4 v[162:165], v[230:231], off offset:528
	s_mov_b64 s[20:21], 0x80000
	v_lshl_add_u64 v[234:235], v[140:141], 0, s[20:21]
	v_lshl_add_u64 v[232:233], s[48:49], 0, v[234:235]
	s_waitcnt vmcnt(16)
	v_pk_add_f32 v[62:63], v[62:63], v[166:167]
	v_pk_add_f32 v[64:65], v[64:65], v[168:169]
	global_store_dwordx4 v[232:233], v[62:65], off
	v_pk_add_f32 v[58:59], v[58:59], v[170:171]
	v_pk_add_f32 v[60:61], v[60:61], v[172:173]
	global_store_dwordx4 v[232:233], v[58:61], off offset:16
	v_pk_add_f32 v[54:55], v[54:55], v[174:175]
	v_pk_add_f32 v[56:57], v[56:57], v[176:177]
	global_store_dwordx4 v[232:233], v[54:57], off offset:512
	v_pk_add_f32 v[50:51], v[50:51], v[178:179]
	v_pk_add_f32 v[52:53], v[52:53], v[180:181]
	global_store_dwordx4 v[232:233], v[50:53], off offset:528
	s_mov_b64 s[20:21], 0xb0000
	v_lshl_add_u64 v[234:235], v[140:141], 0, s[20:21]
	v_lshl_add_u64 v[230:231], s[22:23], 0, v[234:235]
	global_load_dwordx4 v[166:169], v[230:231], off
	global_load_dwordx4 v[170:173], v[230:231], off offset:16
	global_load_dwordx4 v[174:177], v[230:231], off offset:512
	global_load_dwordx4 v[178:181], v[230:231], off offset:528
	s_mov_b64 s[20:21], 0x90000
	v_lshl_add_u64 v[234:235], v[140:141], 0, s[20:21]
	v_lshl_add_u64 v[232:233], s[48:49], 0, v[234:235]
	s_waitcnt vmcnt(16)
	v_pk_add_f32 v[46:47], v[46:47], v[182:183]
	v_pk_add_f32 v[48:49], v[48:49], v[184:185]
	global_store_dwordx4 v[232:233], v[46:49], off
	v_pk_add_f32 v[42:43], v[42:43], v[186:187]
	v_pk_add_f32 v[44:45], v[44:45], v[188:189]
	global_store_dwordx4 v[232:233], v[42:45], off offset:16
	v_pk_add_f32 v[38:39], v[38:39], v[218:219]
	v_pk_add_f32 v[40:41], v[40:41], v[220:221]
	global_store_dwordx4 v[232:233], v[38:41], off offset:512
	v_pk_add_f32 v[34:35], v[34:35], v[222:223]
	v_pk_add_f32 v[36:37], v[36:37], v[224:225]
	global_store_dwordx4 v[232:233], v[34:37], off offset:528
	s_mov_b64 s[20:21], 0xa0000
	v_lshl_add_u64 v[234:235], v[140:141], 0, s[20:21]
	v_lshl_add_u64 v[232:233], s[48:49], 0, v[234:235]
	s_waitcnt vmcnt(12)
	v_pk_add_f32 v[30:31], v[30:31], v[150:151]
	v_pk_add_f32 v[32:33], v[32:33], v[152:153]
	global_store_dwordx4 v[232:233], v[30:33], off
	v_pk_add_f32 v[26:27], v[26:27], v[154:155]
	v_pk_add_f32 v[28:29], v[28:29], v[156:157]
	global_store_dwordx4 v[232:233], v[26:29], off offset:16
	v_pk_add_f32 v[22:23], v[22:23], v[158:159]
	v_pk_add_f32 v[24:25], v[24:25], v[160:161]
	global_store_dwordx4 v[232:233], v[22:25], off offset:512
	v_pk_add_f32 v[18:19], v[18:19], v[162:163]
	v_pk_add_f32 v[20:21], v[20:21], v[164:165]
	global_store_dwordx4 v[232:233], v[18:21], off offset:528
	s_mov_b64 s[20:21], 0xb0000
	v_lshl_add_u64 v[234:235], v[140:141], 0, s[20:21]
	v_lshl_add_u64 v[232:233], s[48:49], 0, v[234:235]
	s_waitcnt vmcnt(8)
	v_pk_add_f32 v[14:15], v[14:15], v[166:167]
	v_pk_add_f32 v[16:17], v[16:17], v[168:169]
	global_store_dwordx4 v[232:233], v[14:17], off
	v_pk_add_f32 v[10:11], v[10:11], v[170:171]
	v_pk_add_f32 v[12:13], v[12:13], v[172:173]
	global_store_dwordx4 v[232:233], v[10:13], off offset:16
	v_pk_add_f32 v[6:7], v[6:7], v[174:175]
	v_pk_add_f32 v[8:9], v[8:9], v[176:177]
	global_store_dwordx4 v[232:233], v[6:9], off offset:512
	v_pk_add_f32 v[2:3], v[2:3], v[178:179]
	v_pk_add_f32 v[4:5], v[4:5], v[180:181]
	global_store_dwordx4 v[232:233], v[2:5], off offset:528
	s_mov_b64 s[48:49], -1
	s_andn2_b64 vcc, exec, s[36:37]
	s_cbranch_vccnz .LBB0_234
	s_andn2_b64 vcc, exec, s[0:1]
	s_cbranch_vccnz .LBB0_233
	s_barrier
	s_branch .LBB0_233
